# M6 + G_in/G_up MFMA order: the two k-halves of each accumulator issued back to back (SrcC forwarding chain), same accumulation order
# speedup vs baseline: 1.0017x; 1.0017x over previous
; #define PG8_SB(B) __builtin_amdgcn_rcpf(1.f + expneg(B))
; #define PG8_SB(B) __builtin_amdgcn_rcpf(1.f + expneg(B))
; #define PG8_STAGE(bufoff, gbase, voff) do { _Pragma("unroll") for (int _i = 0; _i < 2; ++_i) \
;         __builtin_amdgcn_global_load_lds((const unsigned*)((const char*)(gbase) + (size_t)_i * qstep + (voff)[0]), (PG8_LAS unsigned*)(lds + (bufoff) + ldsw + _i * 8192), 16, 0, 0); } while (0)
; #define PG8_LDA(dst, b, h) do { _Pragma("unroll") for (int m = 0; m < 4; ++m) _Pragma("unroll") for (int k = 0; k < 2; ++k) dst[m][k] = *(const PG8_LAS bf16x8*)(lds + PG8_SA(b, h) + aoff + m * 2048 + k * 1024); } while (0)
; #define PG8_MMA(ai, bj, At, Bt) do { __builtin_amdgcn_s_setprio(1); _Pragma("unroll") for (int m = 0; m < 4; ++m) _Pragma("unroll") for (int n = 0; n < 2; ++n) _Pragma("unroll") for (int k = 0; k < 2; ++k) \
;         acc[ai][bj][m][n] = __builtin_amdgcn_mfma_f32_16x16x32_bf16(Bt[n][k], At[m][k], acc[ai][bj][m][n], 0, 0, 0); __builtin_amdgcn_s_setprio(0); } while (0)
; #define PG8_WAIT_V89() do { if constexpr (SLIVER) PG8_WAIT_V(9); else PG8_WAIT_V(8); } while (0)
; #define PG8_LDS_S(b) do { if constexpr (SLIVER) { Sf[0] = *(const PG8_LAS bf16x8*)(lds + STAGE_BYTES + (b) * 2048 + soff0); Sf[1] = *(const PG8_LAS bf16x8*)(lds + STAGE_BYTES + (b) * 2048 + (soff0 ^ 64)); } } while (0)
; #define PG8_WAIT_L(n) asm volatile("s_waitcnt lgkmcnt(" #n ")" ::: "memory")
; #define PG8_BAR __builtin_amdgcn_s_barrier()
; #define PG8_SCHED __builtin_amdgcn_sched_barrier(0)
; template <class Epi, class Sched, bool ALIGN_EPI = false, bool SP2 = false, bool SLIVER = false>
; __device__ __forceinline__ void gemm_phase(PG8_LAS unsigned char* lds, const Gemm g, const Sched& S, const Epi& E) {
;     ...
;             PG8_WAIT_V89(); PG8_WAIT_L(0); PG8_BAR; PG8_MMA(0, 0, At, B0); PG8_MMA(0, 1, At, B1); PG8_BAR; PG8_SCHED;
;             PG8_LDA(At, 0, 1); PG8_LDS_S(0); PG8_STAGE(PG8_SB(0, 0), b2, voffB); PG8_STAGE(PG8_SB(0, 1), b2 + hstep, voffB); PG8_STAGE(PG8_SA(0, 0), a2, voffA);
;             PG8_WAIT_V89(); PG8_WAIT_L(0); PG8_BAR; PG8_MMA(1, 0, At, B0); PG8_MMA(1, 1, At, B1); PG8_MMA_S(); PG8_BAR; PG8_SCHED;
.Lgin_skipw0:
	s_waitcnt lgkmcnt(0)
	s_setprio 1
	s_barrier
	v_mfma_f32_16x16x32_bf16 v[126:129], v[136:139], v[174:177], v[126:129]
	v_mfma_f32_16x16x32_bf16 v[126:129], v[140:143], v[180:183], v[126:129]
	v_mfma_f32_16x16x32_bf16 v[122:125], v[150:153], v[174:177], v[122:125]
	v_mfma_f32_16x16x32_bf16 v[122:125], v[154:157], v[180:183], v[122:125]
	v_mfma_f32_16x16x32_bf16 v[114:117], v[136:139], v[184:187], v[114:117]
	v_mfma_f32_16x16x32_bf16 v[114:117], v[140:143], v[188:191], v[114:117]
	v_mfma_f32_16x16x32_bf16 v[106:109], v[150:153], v[184:187], v[106:109]
	v_mfma_f32_16x16x32_bf16 v[106:109], v[154:157], v[188:191], v[106:109]
	v_mfma_f32_16x16x32_bf16 v[98:101], v[136:139], v[192:195], v[98:101]
	v_mfma_f32_16x16x32_bf16 v[98:101], v[140:143], v[196:199], v[98:101]
	v_mfma_f32_16x16x32_bf16 v[90:93], v[150:153], v[192:195], v[90:93]
	v_mfma_f32_16x16x32_bf16 v[90:93], v[154:157], v[196:199], v[90:93]
	v_mfma_f32_16x16x32_bf16 v[82:85], v[136:139], v[200:203], v[82:85]
	v_mfma_f32_16x16x32_bf16 v[82:85], v[140:143], v[210:213], v[82:85]
	v_mfma_f32_16x16x32_bf16 v[74:77], v[150:153], v[200:203], v[74:77]
	v_mfma_f32_16x16x32_bf16 v[74:77], v[154:157], v[210:213], v[74:77]
	s_setprio 0
	s_setprio 1
	v_mfma_f32_16x16x32_bf16 v[118:121], v[158:161], v[174:177], v[118:121]
	v_mfma_f32_16x16x32_bf16 v[118:121], v[162:165], v[180:183], v[118:121]
	v_mfma_f32_16x16x32_bf16 v[110:113], v[166:169], v[174:177], v[110:113]
	v_mfma_f32_16x16x32_bf16 v[110:113], v[170:173], v[180:183], v[110:113]
	v_mfma_f32_16x16x32_bf16 v[102:105], v[158:161], v[184:187], v[102:105]
	v_mfma_f32_16x16x32_bf16 v[102:105], v[162:165], v[188:191], v[102:105]
	v_mfma_f32_16x16x32_bf16 v[94:97], v[166:169], v[184:187], v[94:97]
	v_mfma_f32_16x16x32_bf16 v[94:97], v[170:173], v[188:191], v[94:97]
	v_mfma_f32_16x16x32_bf16 v[86:89], v[158:161], v[192:195], v[86:89]
	v_mfma_f32_16x16x32_bf16 v[86:89], v[162:165], v[196:199], v[86:89]
	v_mfma_f32_16x16x32_bf16 v[78:81], v[166:169], v[192:195], v[78:81]
	v_mfma_f32_16x16x32_bf16 v[78:81], v[170:173], v[196:199], v[78:81]
	v_mfma_f32_16x16x32_bf16 v[70:73], v[158:161], v[200:203], v[70:73]
	v_mfma_f32_16x16x32_bf16 v[70:73], v[162:165], v[210:213], v[70:73]
	v_mfma_f32_16x16x32_bf16 v[66:69], v[166:169], v[200:203], v[66:69]
	v_mfma_f32_16x16x32_bf16 v[66:69], v[170:173], v[210:213], v[66:69]
	s_barrier
	s_setprio 0
	s_add_i32 s77, s77, s53
	s_mov_b32 m0, s77
	ds_read_b128 v[174:177], v149 offset:16384
	ds_read_b128 v[180:183], v149 offset:17408
	ds_read_b128 v[184:187], v149 offset:18432
	ds_read_b128 v[188:191], v149 offset:19456
	ds_read_b128 v[192:195], v149 offset:20480
	ds_read_b128 v[196:199], v149 offset:21504
	ds_read_b128 v[200:203], v149 offset:22528
	ds_read_b128 v[210:213], v149 offset:23552
	global_load_lds_dwordx4 v132, s[78:79]
	s_add_i32 m0, s77, 0x2000
	s_add_i32 s77, s80, s53
	s_add_u32 s58, s78, 0x40000
	s_addc_u32 s59, s79, 0
	global_load_lds_dwordx4 v132, s[58:59]
	s_mov_b32 m0, s77
	s_nop 0
	s_add_u32 s60, s78, 0x80000
	s_addc_u32 s61, s79, 0
	global_load_lds_dwordx4 v132, s[60:61]
	s_add_i32 m0, s77, 0x2000
	s_nop 0
	s_add_u32 s36, s78, 0xc0000
	s_addc_u32 s37, s79, 0
	global_load_lds_dwordx4 v132, s[36:37]
	s_mov_b64 s[46:47], s[62:63]
	s_mov_b32 m0, s91
	s_nop 0
	global_load_lds_dwordx4 v130, s[46:47]
	s_mov_b32 m0, s50
	s_nop 0
	s_add_u32 s58, s46, 0x40000
	s_addc_u32 s59, s47, 0
	global_load_lds_dwordx4 v130, s[58:59]
	s_cmp_eq_u32 s76, s101
	s_cbranch_scc1 .Lgin_skipw1
	s_waitcnt vmcnt(8)
.Lgin_skipw1:
	s_waitcnt lgkmcnt(0)
	s_setprio 1
	s_barrier
	v_mfma_f32_16x16x32_bf16 v[62:65], v[136:139], v[174:177], v[62:65]
	v_mfma_f32_16x16x32_bf16 v[62:65], v[140:143], v[180:183], v[62:65]
	v_mfma_f32_16x16x32_bf16 v[58:61], v[150:153], v[174:177], v[58:61]
	v_mfma_f32_16x16x32_bf16 v[58:61], v[154:157], v[180:183], v[58:61]
	v_mfma_f32_16x16x32_bf16 v[50:53], v[136:139], v[184:187], v[50:53]
	v_mfma_f32_16x16x32_bf16 v[50:53], v[140:143], v[188:191], v[50:53]
	v_mfma_f32_16x16x32_bf16 v[42:45], v[150:153], v[184:187], v[42:45]
	v_mfma_f32_16x16x32_bf16 v[42:45], v[154:157], v[188:191], v[42:45]
	v_mfma_f32_16x16x32_bf16 v[34:37], v[136:139], v[192:195], v[34:37]
	v_mfma_f32_16x16x32_bf16 v[34:37], v[140:143], v[196:199], v[34:37]
	v_mfma_f32_16x16x32_bf16 v[26:29], v[150:153], v[192:195], v[26:29]
	v_mfma_f32_16x16x32_bf16 v[26:29], v[154:157], v[196:199], v[26:29]
	v_mfma_f32_16x16x32_bf16 v[18:21], v[136:139], v[200:203], v[18:21]
	v_mfma_f32_16x16x32_bf16 v[18:21], v[140:143], v[210:213], v[18:21]
	v_mfma_f32_16x16x32_bf16 v[10:13], v[150:153], v[200:203], v[10:13]
	v_mfma_f32_16x16x32_bf16 v[10:13], v[154:157], v[210:213], v[10:13]
	s_setprio 0
	s_setprio 1
	v_mfma_f32_16x16x32_bf16 v[54:57], v[158:161], v[174:177], v[54:57]
	v_mfma_f32_16x16x32_bf16 v[54:57], v[162:165], v[180:183], v[54:57]
	v_mfma_f32_16x16x32_bf16 v[46:49], v[166:169], v[174:177], v[46:49]
	v_mfma_f32_16x16x32_bf16 v[46:49], v[170:173], v[180:183], v[46:49]
	v_mfma_f32_16x16x32_bf16 v[38:41], v[158:161], v[184:187], v[38:41]
	v_mfma_f32_16x16x32_bf16 v[38:41], v[162:165], v[188:191], v[38:41]
	v_mfma_f32_16x16x32_bf16 v[30:33], v[166:169], v[184:187], v[30:33]
	v_mfma_f32_16x16x32_bf16 v[30:33], v[170:173], v[188:191], v[30:33]
	v_mfma_f32_16x16x32_bf16 v[22:25], v[158:161], v[192:195], v[22:25]
	v_mfma_f32_16x16x32_bf16 v[22:25], v[162:165], v[196:199], v[22:25]
	v_mfma_f32_16x16x32_bf16 v[14:17], v[166:169], v[192:195], v[14:17]
	v_mfma_f32_16x16x32_bf16 v[14:17], v[170:173], v[196:199], v[14:17]
	v_mfma_f32_16x16x32_bf16 v[6:9], v[158:161], v[200:203], v[6:9]
	v_mfma_f32_16x16x32_bf16 v[6:9], v[162:165], v[210:213], v[6:9]
	v_mfma_f32_16x16x32_bf16 v[2:5], v[166:169], v[200:203], v[2:5]
	v_mfma_f32_16x16x32_bf16 v[2:5], v[170:173], v[210:213], v[2:5]
	s_barrier
; #define PG8_STAGE(bufoff, gbase, voff) do { _Pragma("unroll") for (int _i = 0; _i < 2; ++_i) \
;         __builtin_amdgcn_global_load_lds((const unsigned*)((const char*)(gbase) + (size_t)_i * qstep + (voff)[0]), (PG8_LAS unsigned*)(lds + (bufoff) + ldsw + _i * 8192), 16, 0, 0); } while (0)
; #define PG8_LDA(dst, b, h) do { _Pragma("unroll") for (int m = 0; m < 4; ++m) _Pragma("unroll") for (int k = 0; k < 2; ++k) dst[m][k] = *(const PG8_LAS bf16x8*)(lds + PG8_SA(b, h) + aoff + m * 2048 + k * 1024); } while (0)
; #define PG8_LDB(dst, b, h) do { _Pragma("unroll") for (int n = 0; n < 2; ++n) _Pragma("unroll") for (int k = 0; k < 2; ++k) dst[n][k] = *(const PG8_LAS bf16x8*)(lds + PG8_SB(b, h) + boff + n * 2048 + k * 1024); } while (0)
; #define PG8_MMA(ai, bj, At, Bt) do { __builtin_amdgcn_s_setprio(1); _Pragma("unroll") for (int m = 0; m < 4; ++m) _Pragma("unroll") for (int n = 0; n < 2; ++n) _Pragma("unroll") for (int k = 0; k < 2; ++k) \
;         acc[ai][bj][m][n] = __builtin_amdgcn_mfma_f32_16x16x32_bf16(Bt[n][k], At[m][k], acc[ai][bj][m][n], 0, 0, 0); __builtin_amdgcn_s_setprio(0); } while (0)
; #define PG8_WAIT_V89() do { if constexpr (SLIVER) PG8_WAIT_V(9); else PG8_WAIT_V(8); } while (0)
; #define PG8_STAGE_S(b, gbase) do { if constexpr (SLIVER) __builtin_amdgcn_global_load_lds((const unsigned*)((const char*)(gbase) + voffS), (PG8_LAS unsigned*)(lds + STAGE_BYTES + (b) * 2048 + wid * 256), 4, 0, 0); } while (0)
; #define PG8_WAIT_L(n) asm volatile("s_waitcnt lgkmcnt(" #n ")" ::: "memory")
; #define PG8_BAR __builtin_amdgcn_s_barrier()
; #define PG8_SCHED __builtin_amdgcn_sched_barrier(0)
; template <class Epi, class Sched, bool ALIGN_EPI = false, bool SP2 = false, bool SLIVER = false>
; __device__ __forceinline__ void gemm_phase(PG8_LAS unsigned char* lds, const Gemm g, const Sched& S, const Epi& E) {
;     ...
;             PG8_WAIT_V89(); PG8_WAIT_L(0); PG8_BAR; PG8_MMA(1, 0, At, B0); PG8_MMA(1, 1, At, B1); PG8_MMA_S(); PG8_BAR; PG8_SCHED;
;             PG8_LDB(B0, 1, 0); PG8_LDB(B1, 1, 1); PG8_SCHED; PG8_LDA(At, 1, 0); PG8_STAGE(PG8_SA(0, 1), a2 + hstep, voffA); PG8_STAGE_S(0, s2);
;             PG8_WAIT_V89(); PG8_WAIT_L(0); PG8_BAR; PG8_MMA(0, 0, At, B0); PG8_MMA(0, 1, At, B1); PG8_BAR; PG8_SCHED;
	s_setprio 0
	s_add_i32 s62, 0, 0x18000
	v_add_u32_e32 v144, s62, v145
	s_add_i32 s63, 0, 0x1c000
	ds_read_b128 v[136:139], v144
	ds_read_b128 v[140:143], v144 offset:1024
	ds_read_b128 v[150:153], v144 offset:2048
	ds_read_b128 v[154:157], v144 offset:3072
	v_add_u32_e32 v144, s63, v145
	ds_read_b128 v[158:161], v144
	ds_read_b128 v[162:165], v144 offset:1024
	ds_read_b128 v[166:169], v144 offset:2048
	ds_read_b128 v[170:173], v144 offset:3072
	s_mov_b32 m0, s51
	ds_read_b128 v[174:177], v149 offset:32768
	ds_read_b128 v[180:183], v149 offset:33792
	ds_read_b128 v[184:187], v149 offset:34816
	ds_read_b128 v[188:191], v149 offset:35840
	ds_read_b128 v[192:195], v149 offset:36864
	ds_read_b128 v[196:199], v149 offset:37888
	ds_read_b128 v[200:203], v149 offset:38912
	ds_read_b128 v[210:213], v149 offset:39936
	s_add_u32 s60, s46, 0x80000
	s_addc_u32 s61, s47, 0
	global_load_lds_dwordx4 v130, s[60:61]
	s_mov_b32 m0, s54
	s_nop 0
	s_add_u32 s36, s46, 0xc0000
	s_addc_u32 s37, s47, 0
	global_load_lds_dwordx4 v130, s[36:37]
	s_waitcnt vmcnt(8)
	s_waitcnt lgkmcnt(0)
	s_setprio 1
	s_barrier
	v_mfma_f32_16x16x32_bf16 v[126:129], v[136:139], v[174:177], v[126:129]
	v_mfma_f32_16x16x32_bf16 v[126:129], v[140:143], v[180:183], v[126:129]
	v_mfma_f32_16x16x32_bf16 v[122:125], v[150:153], v[174:177], v[122:125]
	v_mfma_f32_16x16x32_bf16 v[122:125], v[154:157], v[180:183], v[122:125]
	v_mfma_f32_16x16x32_bf16 v[114:117], v[136:139], v[184:187], v[114:117]
	v_mfma_f32_16x16x32_bf16 v[114:117], v[140:143], v[188:191], v[114:117]
	v_mfma_f32_16x16x32_bf16 v[106:109], v[150:153], v[184:187], v[106:109]
	v_mfma_f32_16x16x32_bf16 v[106:109], v[154:157], v[188:191], v[106:109]
	v_mfma_f32_16x16x32_bf16 v[98:101], v[136:139], v[192:195], v[98:101]
	v_mfma_f32_16x16x32_bf16 v[98:101], v[140:143], v[196:199], v[98:101]
	v_mfma_f32_16x16x32_bf16 v[90:93], v[150:153], v[192:195], v[90:93]
	v_mfma_f32_16x16x32_bf16 v[90:93], v[154:157], v[196:199], v[90:93]
	v_mfma_f32_16x16x32_bf16 v[82:85], v[136:139], v[200:203], v[82:85]
	v_mfma_f32_16x16x32_bf16 v[82:85], v[140:143], v[210:213], v[82:85]
	v_mfma_f32_16x16x32_bf16 v[74:77], v[150:153], v[200:203], v[74:77]
	v_mfma_f32_16x16x32_bf16 v[74:77], v[154:157], v[210:213], v[74:77]
	s_setprio 0
	s_setprio 1
	v_mfma_f32_16x16x32_bf16 v[118:121], v[158:161], v[174:177], v[118:121]
	v_mfma_f32_16x16x32_bf16 v[118:121], v[162:165], v[180:183], v[118:121]
	v_mfma_f32_16x16x32_bf16 v[110:113], v[166:169], v[174:177], v[110:113]
	v_mfma_f32_16x16x32_bf16 v[110:113], v[170:173], v[180:183], v[110:113]
	v_mfma_f32_16x16x32_bf16 v[102:105], v[158:161], v[184:187], v[102:105]
	v_mfma_f32_16x16x32_bf16 v[102:105], v[162:165], v[188:191], v[102:105]
	v_mfma_f32_16x16x32_bf16 v[94:97], v[166:169], v[184:187], v[94:97]
	v_mfma_f32_16x16x32_bf16 v[94:97], v[170:173], v[188:191], v[94:97]
	v_mfma_f32_16x16x32_bf16 v[86:89], v[158:161], v[192:195], v[86:89]
	v_mfma_f32_16x16x32_bf16 v[86:89], v[162:165], v[196:199], v[86:89]
	v_mfma_f32_16x16x32_bf16 v[78:81], v[166:169], v[192:195], v[78:81]
	v_mfma_f32_16x16x32_bf16 v[78:81], v[170:173], v[196:199], v[78:81]
	v_mfma_f32_16x16x32_bf16 v[70:73], v[158:161], v[200:203], v[70:73]
	v_mfma_f32_16x16x32_bf16 v[70:73], v[162:165], v[210:213], v[70:73]
	v_mfma_f32_16x16x32_bf16 v[66:69], v[166:169], v[200:203], v[66:69]
	v_mfma_f32_16x16x32_bf16 v[66:69], v[170:173], v[210:213], v[66:69]
	s_barrier
; #define PG8_SB(B) __builtin_amdgcn_rcpf(1.f + expneg(B))
; #define PG8_SB(B) __builtin_amdgcn_rcpf(1.f + expneg(B))
; #define PG8_STAGE(bufoff, gbase, voff) do { _Pragma("unroll") for (int _i = 0; _i < 2; ++_i) \
;         __builtin_amdgcn_global_load_lds((const unsigned*)((const char*)(gbase) + (size_t)_i * qstep + (voff)[0]), (PG8_LAS unsigned*)(lds + (bufoff) + ldsw + _i * 8192), 16, 0, 0); } while (0)
; #define PG8_LDA(dst, b, h) do { _Pragma("unroll") for (int m = 0; m < 4; ++m) _Pragma("unroll") for (int k = 0; k < 2; ++k) dst[m][k] = *(const PG8_LAS bf16x8*)(lds + PG8_SA(b, h) + aoff + m * 2048 + k * 1024); } while (0)
; #define PG8_MMA(ai, bj, At, Bt) do { __builtin_amdgcn_s_setprio(1); _Pragma("unroll") for (int m = 0; m < 4; ++m) _Pragma("unroll") for (int n = 0; n < 2; ++n) _Pragma("unroll") for (int k = 0; k < 2; ++k) \
;         acc[ai][bj][m][n] = __builtin_amdgcn_mfma_f32_16x16x32_bf16(Bt[n][k], At[m][k], acc[ai][bj][m][n], 0, 0, 0); __builtin_amdgcn_s_setprio(0); } while (0)
; #define PG8_WAIT_V89() do { if constexpr (SLIVER) PG8_WAIT_V(9); else PG8_WAIT_V(8); } while (0)
; #define PG8_LDS_S(b) do { if constexpr (SLIVER) { Sf[0] = *(const PG8_LAS bf16x8*)(lds + STAGE_BYTES + (b) * 2048 + soff0); Sf[1] = *(const PG8_LAS bf16x8*)(lds + STAGE_BYTES + (b) * 2048 + (soff0 ^ 64)); } } while (0)
; #define PG8_WAIT_L(n) asm volatile("s_waitcnt lgkmcnt(" #n ")" ::: "memory")
; #define PG8_BAR __builtin_amdgcn_s_barrier()
; #define PG8_SCHED __builtin_amdgcn_sched_barrier(0)
; template <class Epi, class Sched, bool ALIGN_EPI = false, bool SP2 = false, bool SLIVER = false>
; __device__ __forceinline__ void gemm_phase(PG8_LAS unsigned char* lds, const Gemm g, const Sched& S, const Epi& E) {
;     ...
;             PG8_LDA(At, 1, 1); PG8_LDS_S(1); PG8_STAGE(PG8_SB(1, 0), b3, voffB); PG8_STAGE(PG8_SB(1, 1), b3 + hstep, voffB); PG8_STAGE(PG8_SA(1, 0), a3, voffA);
;             PG8_WAIT_V89(); PG8_WAIT_L(0); PG8_BAR; PG8_MMA(1, 0, At, B0); PG8_MMA(1, 1, At, B1); PG8_MMA_S(); PG8_BAR; PG8_SCHED;
	s_setprio 0
	s_add_i32 s62, s62, s53
	s_mov_b32 m0, s62
	ds_read_b128 v[174:177], v149 offset:49152
	ds_read_b128 v[180:183], v149 offset:50176
	ds_read_b128 v[184:187], v149 offset:51200
	ds_read_b128 v[188:191], v149 offset:52224
	ds_read_b128 v[192:195], v149 offset:53248
	ds_read_b128 v[196:199], v149 offset:54272
	ds_read_b128 v[200:203], v149 offset:55296
	ds_read_b128 v[210:213], v149 offset:56320
	s_add_u32 s58, s78, 0x80
	s_addc_u32 s59, s79, 0
	global_load_lds_dwordx4 v132, s[58:59]
	s_add_i32 m0, s62, 0x2000
	s_add_i32 s62, s63, s53
	s_add_u32 s60, s78, 0x40080
	s_addc_u32 s61, s79, 0
	global_load_lds_dwordx4 v132, s[60:61]
	s_mov_b32 m0, s62
	s_add_u32 s36, s78, 0x80080
	s_addc_u32 s37, s79, 0
	global_load_lds_dwordx4 v132, s[36:37]
	s_add_i32 m0, s62, 0x2000
	s_nop 0
	s_add_u32 s58, s78, 0xc0080
	s_addc_u32 s59, s79, 0
	global_load_lds_dwordx4 v132, s[58:59]
	s_mov_b32 m0, s10
	s_nop 0
	s_add_u32 s60, s46, 0x80
	s_addc_u32 s61, s47, 0
	global_load_lds_dwordx4 v130, s[60:61]
	s_mov_b32 m0, s55
	s_nop 0
	s_add_u32 s36, s46, 0x40080
	s_addc_u32 s37, s47, 0
	global_load_lds_dwordx4 v130, s[36:37]
	s_waitcnt vmcnt(8)
	s_waitcnt lgkmcnt(0)
	s_setprio 1
	s_barrier
	v_mfma_f32_16x16x32_bf16 v[62:65], v[136:139], v[174:177], v[62:65]
	v_mfma_f32_16x16x32_bf16 v[62:65], v[140:143], v[180:183], v[62:65]
	v_mfma_f32_16x16x32_bf16 v[58:61], v[150:153], v[174:177], v[58:61]
	v_mfma_f32_16x16x32_bf16 v[58:61], v[154:157], v[180:183], v[58:61]
	v_mfma_f32_16x16x32_bf16 v[50:53], v[136:139], v[184:187], v[50:53]
	v_mfma_f32_16x16x32_bf16 v[50:53], v[140:143], v[188:191], v[50:53]
	v_mfma_f32_16x16x32_bf16 v[42:45], v[150:153], v[184:187], v[42:45]
	v_mfma_f32_16x16x32_bf16 v[42:45], v[154:157], v[188:191], v[42:45]
	v_mfma_f32_16x16x32_bf16 v[34:37], v[136:139], v[192:195], v[34:37]
	v_mfma_f32_16x16x32_bf16 v[34:37], v[140:143], v[196:199], v[34:37]
	v_mfma_f32_16x16x32_bf16 v[26:29], v[150:153], v[192:195], v[26:29]
	v_mfma_f32_16x16x32_bf16 v[26:29], v[154:157], v[196:199], v[26:29]
	v_mfma_f32_16x16x32_bf16 v[18:21], v[136:139], v[200:203], v[18:21]
	v_mfma_f32_16x16x32_bf16 v[18:21], v[140:143], v[210:213], v[18:21]
	v_mfma_f32_16x16x32_bf16 v[10:13], v[150:153], v[200:203], v[10:13]
	v_mfma_f32_16x16x32_bf16 v[10:13], v[154:157], v[210:213], v[10:13]
	s_setprio 0
	s_setprio 1
	v_mfma_f32_16x16x32_bf16 v[54:57], v[158:161], v[174:177], v[54:57]
	v_mfma_f32_16x16x32_bf16 v[54:57], v[162:165], v[180:183], v[54:57]
	v_mfma_f32_16x16x32_bf16 v[46:49], v[166:169], v[174:177], v[46:49]
	v_mfma_f32_16x16x32_bf16 v[46:49], v[170:173], v[180:183], v[46:49]
	v_mfma_f32_16x16x32_bf16 v[38:41], v[158:161], v[184:187], v[38:41]
	v_mfma_f32_16x16x32_bf16 v[38:41], v[162:165], v[188:191], v[38:41]
	v_mfma_f32_16x16x32_bf16 v[30:33], v[166:169], v[184:187], v[30:33]
	v_mfma_f32_16x16x32_bf16 v[30:33], v[170:173], v[188:191], v[30:33]
	v_mfma_f32_16x16x32_bf16 v[22:25], v[158:161], v[192:195], v[22:25]
	v_mfma_f32_16x16x32_bf16 v[22:25], v[162:165], v[196:199], v[22:25]
	v_mfma_f32_16x16x32_bf16 v[14:17], v[166:169], v[192:195], v[14:17]
	v_mfma_f32_16x16x32_bf16 v[14:17], v[170:173], v[196:199], v[14:17]
	v_mfma_f32_16x16x32_bf16 v[6:9], v[158:161], v[200:203], v[6:9]
	v_mfma_f32_16x16x32_bf16 v[6:9], v[162:165], v[210:213], v[6:9]
	v_mfma_f32_16x16x32_bf16 v[2:5], v[166:169], v[200:203], v[2:5]
	v_mfma_f32_16x16x32_bf16 v[2:5], v[170:173], v[210:213], v[2:5]
	s_barrier
	s_setprio 0
	s_add_i32 s76, s76, 2
	s_add_u32 s40, s40, 0x100
	s_addc_u32 s41, s41, 0
	s_add_u32 s68, s68, 0x100
	s_addc_u32 s69, s69, 0
	s_cmp_gt_u32 s76, 29
	s_cbranch_scc0 .LBB0_153
	s_and_b64 vcc, exec, s[48:49]
	s_cbranch_vccz .LBB0_156
	s_barrier

; #define PG8_SB(B) __builtin_amdgcn_rcpf(1.f + expneg(B))
; #define PG8_SB(B) __builtin_amdgcn_rcpf(1.f + expneg(B))
; #define PG8_STAGE(bufoff, gbase, voff) do { _Pragma("unroll") for (int _i = 0; _i < 2; ++_i) \
;         __builtin_amdgcn_global_load_lds((const unsigned*)((const char*)(gbase) + (size_t)_i * qstep + (voff)[0]), (PG8_LAS unsigned*)(lds + (bufoff) + ldsw + _i * 8192), 16, 0, 0); } while (0)
; #define PG8_LDA(dst, b, h) do { _Pragma("unroll") for (int m = 0; m < 4; ++m) _Pragma("unroll") for (int k = 0; k < 2; ++k) dst[m][k] = *(const PG8_LAS bf16x8*)(lds + PG8_SA(b, h) + aoff + m * 2048 + k * 1024); } while (0)
; #define PG8_MMA(ai, bj, At, Bt) do { __builtin_amdgcn_s_setprio(1); _Pragma("unroll") for (int m = 0; m < 4; ++m) _Pragma("unroll") for (int n = 0; n < 2; ++n) _Pragma("unroll") for (int k = 0; k < 2; ++k) \
;         acc[ai][bj][m][n] = __builtin_amdgcn_mfma_f32_16x16x32_bf16(Bt[n][k], At[m][k], acc[ai][bj][m][n], 0, 0, 0); __builtin_amdgcn_s_setprio(0); } while (0)
; #define PG8_WAIT_V89() do { if constexpr (SLIVER) PG8_WAIT_V(9); else PG8_WAIT_V(8); } while (0)
; #define PG8_LDS_S(b) do { if constexpr (SLIVER) { Sf[0] = *(const PG8_LAS bf16x8*)(lds + STAGE_BYTES + (b) * 2048 + soff0); Sf[1] = *(const PG8_LAS bf16x8*)(lds + STAGE_BYTES + (b) * 2048 + (soff0 ^ 64)); } } while (0)
; #define PG8_WAIT_L(n) asm volatile("s_waitcnt lgkmcnt(" #n ")" ::: "memory")
; #define PG8_BAR __builtin_amdgcn_s_barrier()
; #define PG8_SCHED __builtin_amdgcn_sched_barrier(0)
; template <class Epi, class Sched, bool ALIGN_EPI = false, bool SP2 = false, bool SLIVER = false>
; __device__ __forceinline__ void gemm_phase(PG8_LAS unsigned char* lds, const Gemm g, const Sched& S, const Epi& E) {
;     ...
;             PG8_WAIT_V89(); PG8_WAIT_L(0); PG8_BAR; PG8_MMA(0, 0, At, B0); PG8_MMA(0, 1, At, B1); PG8_BAR; PG8_SCHED;
;             PG8_LDA(At, 0, 1); PG8_LDS_S(0); PG8_STAGE(PG8_SB(0, 0), b2, voffB); PG8_STAGE(PG8_SB(0, 1), b2 + hstep, voffB); PG8_STAGE(PG8_SA(0, 0), a2, voffA);
;             PG8_WAIT_V89(); PG8_WAIT_L(0); PG8_BAR; PG8_MMA(1, 0, At, B0); PG8_MMA(1, 1, At, B1); PG8_MMA_S(); PG8_BAR; PG8_SCHED;
.Lgup_skipw0:
	s_waitcnt lgkmcnt(0)
	s_setprio 1
	s_barrier
	v_mfma_f32_16x16x32_bf16 v[126:129], v[130:133], v[172:175], v[126:129]
	v_mfma_f32_16x16x32_bf16 v[126:129], v[138:141], v[180:183], v[126:129]
	v_mfma_f32_16x16x32_bf16 v[118:121], v[148:151], v[172:175], v[118:121]
	v_mfma_f32_16x16x32_bf16 v[118:121], v[152:155], v[180:183], v[118:121]
	v_mfma_f32_16x16x32_bf16 v[110:113], v[130:133], v[184:187], v[110:113]
	v_mfma_f32_16x16x32_bf16 v[110:113], v[138:141], v[188:191], v[110:113]
	v_mfma_f32_16x16x32_bf16 v[102:105], v[148:151], v[184:187], v[102:105]
	v_mfma_f32_16x16x32_bf16 v[102:105], v[152:155], v[188:191], v[102:105]
	v_mfma_f32_16x16x32_bf16 v[94:97], v[130:133], v[192:195], v[94:97]
	v_mfma_f32_16x16x32_bf16 v[94:97], v[138:141], v[196:199], v[94:97]
	v_mfma_f32_16x16x32_bf16 v[86:89], v[148:151], v[192:195], v[86:89]
	v_mfma_f32_16x16x32_bf16 v[86:89], v[152:155], v[196:199], v[86:89]
	v_mfma_f32_16x16x32_bf16 v[78:81], v[130:133], v[200:203], v[78:81]
	v_mfma_f32_16x16x32_bf16 v[78:81], v[138:141], v[210:213], v[78:81]
	v_mfma_f32_16x16x32_bf16 v[70:73], v[148:151], v[200:203], v[70:73]
	v_mfma_f32_16x16x32_bf16 v[70:73], v[152:155], v[210:213], v[70:73]
	s_setprio 0
	s_setprio 1
	v_mfma_f32_16x16x32_bf16 v[122:125], v[156:159], v[172:175], v[122:125]
	v_mfma_f32_16x16x32_bf16 v[122:125], v[160:163], v[180:183], v[122:125]
	v_mfma_f32_16x16x32_bf16 v[114:117], v[164:167], v[172:175], v[114:117]
	v_mfma_f32_16x16x32_bf16 v[114:117], v[168:171], v[180:183], v[114:117]
	v_mfma_f32_16x16x32_bf16 v[106:109], v[156:159], v[184:187], v[106:109]
	v_mfma_f32_16x16x32_bf16 v[106:109], v[160:163], v[188:191], v[106:109]
	v_mfma_f32_16x16x32_bf16 v[98:101], v[164:167], v[184:187], v[98:101]
	v_mfma_f32_16x16x32_bf16 v[98:101], v[168:171], v[188:191], v[98:101]
	v_mfma_f32_16x16x32_bf16 v[90:93], v[156:159], v[192:195], v[90:93]
	v_mfma_f32_16x16x32_bf16 v[90:93], v[160:163], v[196:199], v[90:93]
	v_mfma_f32_16x16x32_bf16 v[82:85], v[164:167], v[192:195], v[82:85]
	v_mfma_f32_16x16x32_bf16 v[82:85], v[168:171], v[196:199], v[82:85]
	v_mfma_f32_16x16x32_bf16 v[74:77], v[156:159], v[200:203], v[74:77]
	v_mfma_f32_16x16x32_bf16 v[74:77], v[160:163], v[210:213], v[74:77]
	v_mfma_f32_16x16x32_bf16 v[66:69], v[164:167], v[200:203], v[66:69]
	v_mfma_f32_16x16x32_bf16 v[66:69], v[168:171], v[210:213], v[66:69]
	s_barrier
	s_setprio 0
	s_mov_b64 s[46:47], s[76:77]
	s_add_i32 s76, s78, s88
	s_mov_b32 m0, s76
	ds_read_b128 v[172:175], v147 offset:16384
	ds_read_b128 v[180:183], v147 offset:17408
	ds_read_b128 v[184:187], v147 offset:18432
	ds_read_b128 v[188:191], v147 offset:19456
	ds_read_b128 v[192:195], v147 offset:20480
	ds_read_b128 v[196:199], v147 offset:21504
	ds_read_b128 v[200:203], v147 offset:22528
	ds_read_b128 v[210:213], v147 offset:23552
	global_load_lds_dwordx4 v178, s[46:47]
	s_add_i32 m0, s76, 0x2000
	s_add_i32 s76, s79, s88
	s_add_u32 s58, s46, 0x40000
	s_addc_u32 s59, s47, 0
	global_load_lds_dwordx4 v178, s[58:59]
	s_mov_b32 m0, s76
	s_nop 0
	s_add_u32 s60, s46, 0x80000
	s_addc_u32 s61, s47, 0
	global_load_lds_dwordx4 v178, s[60:61]
	s_add_i32 m0, s76, 0x2000
	s_nop 0
	s_add_u32 s36, s46, 0xc0000
	s_addc_u32 s37, s47, 0
	global_load_lds_dwordx4 v178, s[36:37]
	s_mov_b32 m0, s45
	s_nop 0
	global_load_lds_dwordx4 v134, s[80:81]
	s_mov_b32 m0, s83
	s_nop 0
	s_add_u32 s58, s80, 0x40000
	s_addc_u32 s59, s81, 0
	global_load_lds_dwordx4 v134, s[58:59]
	s_cmp_eq_u32 s69, s101
	s_cbranch_scc1 .Lgup_skipw1
	s_waitcnt vmcnt(8)
.Lgup_skipw1:
	s_waitcnt lgkmcnt(0)
	s_setprio 1
	s_barrier
	v_mfma_f32_16x16x32_bf16 v[62:65], v[130:133], v[172:175], v[62:65]
	v_mfma_f32_16x16x32_bf16 v[62:65], v[138:141], v[180:183], v[62:65]
	v_mfma_f32_16x16x32_bf16 v[54:57], v[148:151], v[172:175], v[54:57]
	v_mfma_f32_16x16x32_bf16 v[54:57], v[152:155], v[180:183], v[54:57]
	v_mfma_f32_16x16x32_bf16 v[46:49], v[130:133], v[184:187], v[46:49]
	v_mfma_f32_16x16x32_bf16 v[46:49], v[138:141], v[188:191], v[46:49]
	v_mfma_f32_16x16x32_bf16 v[38:41], v[148:151], v[184:187], v[38:41]
	v_mfma_f32_16x16x32_bf16 v[38:41], v[152:155], v[188:191], v[38:41]
	v_mfma_f32_16x16x32_bf16 v[30:33], v[130:133], v[192:195], v[30:33]
	v_mfma_f32_16x16x32_bf16 v[30:33], v[138:141], v[196:199], v[30:33]
	v_mfma_f32_16x16x32_bf16 v[22:25], v[148:151], v[192:195], v[22:25]
	v_mfma_f32_16x16x32_bf16 v[22:25], v[152:155], v[196:199], v[22:25]
	v_mfma_f32_16x16x32_bf16 v[14:17], v[130:133], v[200:203], v[14:17]
	v_mfma_f32_16x16x32_bf16 v[14:17], v[138:141], v[210:213], v[14:17]
	v_mfma_f32_16x16x32_bf16 v[6:9], v[148:151], v[200:203], v[6:9]
	v_mfma_f32_16x16x32_bf16 v[6:9], v[152:155], v[210:213], v[6:9]
	s_setprio 0
	s_setprio 1
	v_mfma_f32_16x16x32_bf16 v[58:61], v[156:159], v[172:175], v[58:61]
	v_mfma_f32_16x16x32_bf16 v[58:61], v[160:163], v[180:183], v[58:61]
	v_mfma_f32_16x16x32_bf16 v[50:53], v[164:167], v[172:175], v[50:53]
	v_mfma_f32_16x16x32_bf16 v[50:53], v[168:171], v[180:183], v[50:53]
	v_mfma_f32_16x16x32_bf16 v[42:45], v[156:159], v[184:187], v[42:45]
	v_mfma_f32_16x16x32_bf16 v[42:45], v[160:163], v[188:191], v[42:45]
	v_mfma_f32_16x16x32_bf16 v[34:37], v[164:167], v[184:187], v[34:37]
	v_mfma_f32_16x16x32_bf16 v[34:37], v[168:171], v[188:191], v[34:37]
	v_mfma_f32_16x16x32_bf16 v[26:29], v[156:159], v[192:195], v[26:29]
	v_mfma_f32_16x16x32_bf16 v[26:29], v[160:163], v[196:199], v[26:29]
	v_mfma_f32_16x16x32_bf16 v[18:21], v[164:167], v[192:195], v[18:21]
	v_mfma_f32_16x16x32_bf16 v[18:21], v[168:171], v[196:199], v[18:21]
	v_mfma_f32_16x16x32_bf16 v[10:13], v[156:159], v[200:203], v[10:13]
	v_mfma_f32_16x16x32_bf16 v[10:13], v[160:163], v[210:213], v[10:13]
	v_mfma_f32_16x16x32_bf16 v[2:5], v[164:167], v[200:203], v[2:5]
	v_mfma_f32_16x16x32_bf16 v[2:5], v[168:171], v[210:213], v[2:5]
	s_barrier
; #define PG8_STAGE(bufoff, gbase, voff) do { _Pragma("unroll") for (int _i = 0; _i < 2; ++_i) \
;         __builtin_amdgcn_global_load_lds((const unsigned*)((const char*)(gbase) + (size_t)_i * qstep + (voff)[0]), (PG8_LAS unsigned*)(lds + (bufoff) + ldsw + _i * 8192), 16, 0, 0); } while (0)
; #define PG8_LDA(dst, b, h) do { _Pragma("unroll") for (int m = 0; m < 4; ++m) _Pragma("unroll") for (int k = 0; k < 2; ++k) dst[m][k] = *(const PG8_LAS bf16x8*)(lds + PG8_SA(b, h) + aoff + m * 2048 + k * 1024); } while (0)
; #define PG8_LDB(dst, b, h) do { _Pragma("unroll") for (int n = 0; n < 2; ++n) _Pragma("unroll") for (int k = 0; k < 2; ++k) dst[n][k] = *(const PG8_LAS bf16x8*)(lds + PG8_SB(b, h) + boff + n * 2048 + k * 1024); } while (0)
; #define PG8_MMA(ai, bj, At, Bt) do { __builtin_amdgcn_s_setprio(1); _Pragma("unroll") for (int m = 0; m < 4; ++m) _Pragma("unroll") for (int n = 0; n < 2; ++n) _Pragma("unroll") for (int k = 0; k < 2; ++k) \
;         acc[ai][bj][m][n] = __builtin_amdgcn_mfma_f32_16x16x32_bf16(Bt[n][k], At[m][k], acc[ai][bj][m][n], 0, 0, 0); __builtin_amdgcn_s_setprio(0); } while (0)
; #define PG8_WAIT_V89() do { if constexpr (SLIVER) PG8_WAIT_V(9); else PG8_WAIT_V(8); } while (0)
; #define PG8_STAGE_S(b, gbase) do { if constexpr (SLIVER) __builtin_amdgcn_global_load_lds((const unsigned*)((const char*)(gbase) + voffS), (PG8_LAS unsigned*)(lds + STAGE_BYTES + (b) * 2048 + wid * 256), 4, 0, 0); } while (0)
; #define PG8_WAIT_L(n) asm volatile("s_waitcnt lgkmcnt(" #n ")" ::: "memory")
; #define PG8_BAR __builtin_amdgcn_s_barrier()
; #define PG8_SCHED __builtin_amdgcn_sched_barrier(0)
; template <class Epi, class Sched, bool ALIGN_EPI = false, bool SP2 = false, bool SLIVER = false>
; __device__ __forceinline__ void gemm_phase(PG8_LAS unsigned char* lds, const Gemm g, const Sched& S, const Epi& E) {
;     ...
;             PG8_WAIT_V89(); PG8_WAIT_L(0); PG8_BAR; PG8_MMA(1, 0, At, B0); PG8_MMA(1, 1, At, B1); PG8_MMA_S(); PG8_BAR; PG8_SCHED;
;             PG8_LDB(B0, 1, 0); PG8_LDB(B1, 1, 1); PG8_SCHED; PG8_LDA(At, 1, 0); PG8_STAGE(PG8_SA(0, 1), a2 + hstep, voffA); PG8_STAGE_S(0, s2);
;             PG8_WAIT_V89(); PG8_WAIT_L(0); PG8_BAR; PG8_MMA(0, 0, At, B0); PG8_MMA(0, 1, At, B1); PG8_BAR; PG8_SCHED;
	s_setprio 0
	s_add_i32 s76, 0, 0x18000
	v_add_u32_e32 v142, s76, v143
	s_add_i32 s77, 0, 0x1c000
	ds_read_b128 v[130:133], v142
	ds_read_b128 v[138:141], v142 offset:1024
	ds_read_b128 v[148:151], v142 offset:2048
	ds_read_b128 v[152:155], v142 offset:3072
	v_add_u32_e32 v142, s77, v143
	ds_read_b128 v[156:159], v142
	ds_read_b128 v[160:163], v142 offset:1024
	ds_read_b128 v[164:167], v142 offset:2048
	ds_read_b128 v[168:171], v142 offset:3072
	s_mov_b32 m0, s90
	ds_read_b128 v[172:175], v147 offset:32768
	ds_read_b128 v[180:183], v147 offset:33792
	ds_read_b128 v[184:187], v147 offset:34816
	ds_read_b128 v[188:191], v147 offset:35840
	ds_read_b128 v[192:195], v147 offset:36864
	ds_read_b128 v[196:199], v147 offset:37888
	ds_read_b128 v[200:203], v147 offset:38912
	ds_read_b128 v[210:213], v147 offset:39936
	s_add_u32 s60, s80, 0x80000
	s_addc_u32 s61, s81, 0
	global_load_lds_dwordx4 v134, s[60:61]
	s_mov_b32 m0, s91
	s_nop 0
	s_add_u32 s36, s80, 0xc0000
	s_addc_u32 s37, s81, 0
	global_load_lds_dwordx4 v134, s[36:37]
	s_waitcnt vmcnt(8)
	s_waitcnt lgkmcnt(0)
	s_setprio 1
	s_barrier
	v_mfma_f32_16x16x32_bf16 v[126:129], v[130:133], v[172:175], v[126:129]
	v_mfma_f32_16x16x32_bf16 v[126:129], v[138:141], v[180:183], v[126:129]
	v_mfma_f32_16x16x32_bf16 v[118:121], v[148:151], v[172:175], v[118:121]
	v_mfma_f32_16x16x32_bf16 v[118:121], v[152:155], v[180:183], v[118:121]
	v_mfma_f32_16x16x32_bf16 v[110:113], v[130:133], v[184:187], v[110:113]
	v_mfma_f32_16x16x32_bf16 v[110:113], v[138:141], v[188:191], v[110:113]
	v_mfma_f32_16x16x32_bf16 v[102:105], v[148:151], v[184:187], v[102:105]
	v_mfma_f32_16x16x32_bf16 v[102:105], v[152:155], v[188:191], v[102:105]
	v_mfma_f32_16x16x32_bf16 v[94:97], v[130:133], v[192:195], v[94:97]
	v_mfma_f32_16x16x32_bf16 v[94:97], v[138:141], v[196:199], v[94:97]
	v_mfma_f32_16x16x32_bf16 v[86:89], v[148:151], v[192:195], v[86:89]
	v_mfma_f32_16x16x32_bf16 v[86:89], v[152:155], v[196:199], v[86:89]
	v_mfma_f32_16x16x32_bf16 v[78:81], v[130:133], v[200:203], v[78:81]
	v_mfma_f32_16x16x32_bf16 v[78:81], v[138:141], v[210:213], v[78:81]
	v_mfma_f32_16x16x32_bf16 v[70:73], v[148:151], v[200:203], v[70:73]
	v_mfma_f32_16x16x32_bf16 v[70:73], v[152:155], v[210:213], v[70:73]
	s_setprio 0
	s_setprio 1
	v_mfma_f32_16x16x32_bf16 v[122:125], v[156:159], v[172:175], v[122:125]
	v_mfma_f32_16x16x32_bf16 v[122:125], v[160:163], v[180:183], v[122:125]
	v_mfma_f32_16x16x32_bf16 v[114:117], v[164:167], v[172:175], v[114:117]
	v_mfma_f32_16x16x32_bf16 v[114:117], v[168:171], v[180:183], v[114:117]
	v_mfma_f32_16x16x32_bf16 v[106:109], v[156:159], v[184:187], v[106:109]
	v_mfma_f32_16x16x32_bf16 v[106:109], v[160:163], v[188:191], v[106:109]
	v_mfma_f32_16x16x32_bf16 v[98:101], v[164:167], v[184:187], v[98:101]
	v_mfma_f32_16x16x32_bf16 v[98:101], v[168:171], v[188:191], v[98:101]
	v_mfma_f32_16x16x32_bf16 v[90:93], v[156:159], v[192:195], v[90:93]
	v_mfma_f32_16x16x32_bf16 v[90:93], v[160:163], v[196:199], v[90:93]
	v_mfma_f32_16x16x32_bf16 v[82:85], v[164:167], v[192:195], v[82:85]
	v_mfma_f32_16x16x32_bf16 v[82:85], v[168:171], v[196:199], v[82:85]
	v_mfma_f32_16x16x32_bf16 v[74:77], v[156:159], v[200:203], v[74:77]
	v_mfma_f32_16x16x32_bf16 v[74:77], v[160:163], v[210:213], v[74:77]
	v_mfma_f32_16x16x32_bf16 v[66:69], v[164:167], v[200:203], v[66:69]
	v_mfma_f32_16x16x32_bf16 v[66:69], v[168:171], v[210:213], v[66:69]
	s_barrier
; #define PG8_SB(B) __builtin_amdgcn_rcpf(1.f + expneg(B))
; #define PG8_SB(B) __builtin_amdgcn_rcpf(1.f + expneg(B))
; #define PG8_STAGE(bufoff, gbase, voff) do { _Pragma("unroll") for (int _i = 0; _i < 2; ++_i) \
;         __builtin_amdgcn_global_load_lds((const unsigned*)((const char*)(gbase) + (size_t)_i * qstep + (voff)[0]), (PG8_LAS unsigned*)(lds + (bufoff) + ldsw + _i * 8192), 16, 0, 0); } while (0)
; #define PG8_LDA(dst, b, h) do { _Pragma("unroll") for (int m = 0; m < 4; ++m) _Pragma("unroll") for (int k = 0; k < 2; ++k) dst[m][k] = *(const PG8_LAS bf16x8*)(lds + PG8_SA(b, h) + aoff + m * 2048 + k * 1024); } while (0)
; #define PG8_MMA(ai, bj, At, Bt) do { __builtin_amdgcn_s_setprio(1); _Pragma("unroll") for (int m = 0; m < 4; ++m) _Pragma("unroll") for (int n = 0; n < 2; ++n) _Pragma("unroll") for (int k = 0; k < 2; ++k) \
;         acc[ai][bj][m][n] = __builtin_amdgcn_mfma_f32_16x16x32_bf16(Bt[n][k], At[m][k], acc[ai][bj][m][n], 0, 0, 0); __builtin_amdgcn_s_setprio(0); } while (0)
; #define PG8_WAIT_V89() do { if constexpr (SLIVER) PG8_WAIT_V(9); else PG8_WAIT_V(8); } while (0)
; #define PG8_LDS_S(b) do { if constexpr (SLIVER) { Sf[0] = *(const PG8_LAS bf16x8*)(lds + STAGE_BYTES + (b) * 2048 + soff0); Sf[1] = *(const PG8_LAS bf16x8*)(lds + STAGE_BYTES + (b) * 2048 + (soff0 ^ 64)); } } while (0)
; #define PG8_WAIT_L(n) asm volatile("s_waitcnt lgkmcnt(" #n ")" ::: "memory")
; #define PG8_BAR __builtin_amdgcn_s_barrier()
; #define PG8_SCHED __builtin_amdgcn_sched_barrier(0)
; template <class Epi, class Sched, bool ALIGN_EPI = false, bool SP2 = false, bool SLIVER = false>
; __device__ __forceinline__ void gemm_phase(PG8_LAS unsigned char* lds, const Gemm g, const Sched& S, const Epi& E) {
;     ...
;             PG8_LDA(At, 1, 1); PG8_LDS_S(1); PG8_STAGE(PG8_SB(1, 0), b3, voffB); PG8_STAGE(PG8_SB(1, 1), b3 + hstep, voffB); PG8_STAGE(PG8_SA(1, 0), a3, voffA);
;             PG8_WAIT_V89(); PG8_WAIT_L(0); PG8_BAR; PG8_MMA(1, 0, At, B0); PG8_MMA(1, 1, At, B1); PG8_MMA_S(); PG8_BAR; PG8_SCHED;
	s_setprio 0
	s_add_i32 s76, s76, s88
	s_mov_b32 m0, s76
	ds_read_b128 v[172:175], v147 offset:49152
	ds_read_b128 v[180:183], v147 offset:50176
	ds_read_b128 v[184:187], v147 offset:51200
	ds_read_b128 v[188:191], v147 offset:52224
	ds_read_b128 v[192:195], v147 offset:53248
	ds_read_b128 v[196:199], v147 offset:54272
	ds_read_b128 v[200:203], v147 offset:55296
	ds_read_b128 v[210:213], v147 offset:56320
	s_add_u32 s58, s46, 0x80
	s_addc_u32 s59, s47, 0
	global_load_lds_dwordx4 v178, s[58:59]
	s_add_i32 m0, s76, 0x2000
	s_add_i32 s76, s77, s88
	s_add_u32 s60, s46, 0x40080
	s_addc_u32 s61, s47, 0
	global_load_lds_dwordx4 v178, s[60:61]
	s_mov_b32 m0, s76
	s_add_u32 s36, s46, 0x80080
	s_addc_u32 s37, s47, 0
	global_load_lds_dwordx4 v178, s[36:37]
	s_add_i32 m0, s76, 0x2000
	s_nop 0
	s_add_u32 s58, s46, 0xc0080
	s_addc_u32 s59, s47, 0
	global_load_lds_dwordx4 v178, s[58:59]
	s_mov_b32 m0, s93
	s_nop 0
	s_add_u32 s60, s80, 0x80
	s_addc_u32 s61, s81, 0
	global_load_lds_dwordx4 v134, s[60:61]
	s_mov_b32 m0, s94
	s_nop 0
	s_add_u32 s36, s80, 0x40080
	s_addc_u32 s37, s81, 0
	global_load_lds_dwordx4 v134, s[36:37]
	s_waitcnt vmcnt(8)
	s_waitcnt lgkmcnt(0)
	s_setprio 1
	s_barrier
	v_mfma_f32_16x16x32_bf16 v[62:65], v[130:133], v[172:175], v[62:65]
	v_mfma_f32_16x16x32_bf16 v[62:65], v[138:141], v[180:183], v[62:65]
	v_mfma_f32_16x16x32_bf16 v[54:57], v[148:151], v[172:175], v[54:57]
	v_mfma_f32_16x16x32_bf16 v[54:57], v[152:155], v[180:183], v[54:57]
	v_mfma_f32_16x16x32_bf16 v[46:49], v[130:133], v[184:187], v[46:49]
	v_mfma_f32_16x16x32_bf16 v[46:49], v[138:141], v[188:191], v[46:49]
	v_mfma_f32_16x16x32_bf16 v[38:41], v[148:151], v[184:187], v[38:41]
	v_mfma_f32_16x16x32_bf16 v[38:41], v[152:155], v[188:191], v[38:41]
	v_mfma_f32_16x16x32_bf16 v[30:33], v[130:133], v[192:195], v[30:33]
	v_mfma_f32_16x16x32_bf16 v[30:33], v[138:141], v[196:199], v[30:33]
	v_mfma_f32_16x16x32_bf16 v[22:25], v[148:151], v[192:195], v[22:25]
	v_mfma_f32_16x16x32_bf16 v[22:25], v[152:155], v[196:199], v[22:25]
	v_mfma_f32_16x16x32_bf16 v[14:17], v[130:133], v[200:203], v[14:17]
	v_mfma_f32_16x16x32_bf16 v[14:17], v[138:141], v[210:213], v[14:17]
	v_mfma_f32_16x16x32_bf16 v[6:9], v[148:151], v[200:203], v[6:9]
	v_mfma_f32_16x16x32_bf16 v[6:9], v[152:155], v[210:213], v[6:9]
	s_setprio 0
	s_setprio 1
	v_mfma_f32_16x16x32_bf16 v[58:61], v[156:159], v[172:175], v[58:61]
	v_mfma_f32_16x16x32_bf16 v[58:61], v[160:163], v[180:183], v[58:61]
	v_mfma_f32_16x16x32_bf16 v[50:53], v[164:167], v[172:175], v[50:53]
	v_mfma_f32_16x16x32_bf16 v[50:53], v[168:171], v[180:183], v[50:53]
	v_mfma_f32_16x16x32_bf16 v[42:45], v[156:159], v[184:187], v[42:45]
	v_mfma_f32_16x16x32_bf16 v[42:45], v[160:163], v[188:191], v[42:45]
	v_mfma_f32_16x16x32_bf16 v[34:37], v[164:167], v[184:187], v[34:37]
	v_mfma_f32_16x16x32_bf16 v[34:37], v[168:171], v[188:191], v[34:37]
	v_mfma_f32_16x16x32_bf16 v[26:29], v[156:159], v[192:195], v[26:29]
	v_mfma_f32_16x16x32_bf16 v[26:29], v[160:163], v[196:199], v[26:29]
	v_mfma_f32_16x16x32_bf16 v[18:21], v[164:167], v[192:195], v[18:21]
	v_mfma_f32_16x16x32_bf16 v[18:21], v[168:171], v[196:199], v[18:21]
	v_mfma_f32_16x16x32_bf16 v[10:13], v[156:159], v[200:203], v[10:13]
	v_mfma_f32_16x16x32_bf16 v[10:13], v[160:163], v[210:213], v[10:13]
	v_mfma_f32_16x16x32_bf16 v[2:5], v[164:167], v[200:203], v[2:5]
	v_mfma_f32_16x16x32_bf16 v[2:5], v[168:171], v[210:213], v[2:5]
	s_barrier
	s_setprio 0
	s_add_i32 s69, s69, 2
	s_add_u32 s62, s62, 0x100
	s_addc_u32 s63, s63, 0
	s_add_u32 s67, s67, 0x100
	s_addc_u32 s68, s68, 0
	s_cmp_gt_u32 s69, 29
	s_cbranch_scc0 .LBB0_705
	s_and_b64 vcc, exec, s[42:43]
	s_cbranch_vccz .LBB0_708
	s_barrier
